# mLSTM chain: C-state bf16 staging writes as straight-line exec-masked code (packed cvt) instead of 24 branchy blocks; top-of-chunk wait leaves the 4 output stores in flight
# speedup vs baseline: 1.0944x; 1.0149x over previous
; #define LAS __attribute__((address_space(3)))
; __device__ __forceinline__ void mlstm_task(const Ctx& c, int p, int l, int q, int h, int slab) {
;     bf16_t* Z = (bf16_t*)(wsg(c) + WS_Z); const float* gif = (const float*)(wsg(c) + WS_GIF);
;     const bf16_t* SLp = (const bf16_t*)(wsg(c) + WS_SL) + (size_t)(q < 2 ? q * 512 + h * 128 : 1024 + (q - 2) * 4 + h) * 4096 + (c.tid >> 3) * 64 + 8 * (c.tid & 7);
;     const Seq sq = seq_of(p, q); const int tid = c.tid, lane = c.lane, w = c.wave;
;     LAS bf16_t* Qs = (LAS bf16_t*)(c.lds); LAS bf16_t* Ks = (LAS bf16_t*)(c.lds + 33792); LAS bf16_t* KT = (LAS bf16_t*)(c.lds + 67584); LAS bf16_t* VT = (LAS bf16_t*)(c.lds + 104448);
;     LAS bf16_t* VgT = (LAS bf16_t*)(c.lds + 109200); LAS bf16_t* Cs = (LAS bf16_t*)(c.lds + 113952); LAS bf16_t* St = (LAS bf16_t*)(c.lds + 131376);
;     LAS float* sc = (LAS float*)(c.lds + 140592);
;     LAS float* bcum = sc; LAS float* igs = sc + 64; LAS float* mts = sc + 128; LAS float* wint = sc + 192; LAS float* gsrc = sc + 256; LAS float* dd = sc + 320; LAS float* misc = sc + 384; LAS float* esc = sc + 392;
;     const int nvalid = sq.sample ? DSEQ : 64, nch = sq.sample ? 1 : SEQ / 64;
;     const float bi = inp(c, I_IFB)[l * 8 + h], bf = inp(c, I_IFB)[l * 8 + 4 + h];
;     f32x4 cacc[3][2];
; #pragma unroll
;     for (int vi = 0; vi < 3; ++vi)
; #pragma unroll
;         for (int e = 0; e < 2; ++e)
; #pragma unroll
;             for (int r = 0; r < 4; ++r) {
;                 const int vloc = 16 * vi + (lane >> 4) * 4 + r, d = 16 * (2 * w + e) + (lane & 15); float v0 = 0.f;
;                 if (sq.sample) { if (vloc < 32) v0 = inp(c, I_SMC)[(((size_t)l * DB + sq.b) * 4 + h) * 65536 + (size_t)(slab * 32 + vloc) * 256 + d];
;                                  else if (vloc == 32) v0 = inp(c, I_SMN)[(((size_t)l * DB + sq.b) * 4 + h) * 256 + d]; }
;                 cacc[vi][e][r] = v0;
;             }
;     if (tid < 64) VT[32 * 72 + tid] = (bf16_t)0x3f80u;
;     if (tid == 0) misc[0] = sq.sample ? inp(c, I_SMM)[((size_t)l * DB + sq.b) * 4 + h] : 0.f;
;     unsigned zz = 0u; asm volatile("" : "+v"(zz)); const u32x4 zv = {zz, zz, zz, zz};
;     u32x4 pq[4], pk[4], pvv = zv, psl = zv; float pgi = 0.f, pgf = 0.f; int pfc = 0;
;     ...
;     ML_PREFETCH(sq.row0);
;     __syncthreads();
.LBB0_1582:
	s_or_b64 exec, exec, s[18:19]
	s_mov_b64 s[18:19], 0x1e0f4100
	v_readlane_b32 s36, v254, 42
	v_lshl_add_u64 v[92:93], v[2:3], 0, s[18:19]
	s_add_i32 s28, s84, 0x1bd20
	v_lshl_add_u32 v2, v11, 1, s84
	v_lshrrev_b32_e32 v11, 3, v183
	s_lshl_b32 s34, s36, 6
	v_and_b32_e32 v90, 15, v182
	s_add_i32 s30, s84, 0x10800
	s_add_i32 s31, s84, 0x20130
	v_mul_lo_u32 v11, v11, s81
	s_add_i32 s34, s28, s34
	v_add3_u32 v118, s31, v11, v0
	v_lshl_add_u32 v0, v90, 1, s34
	v_and_b32_e32 v11, 0x7f, v183
	v_mov_b32_e32 v62, s30
	s_movk_i32 s34, 0x120
	v_lshl_add_u32 v61, v11, 2, s84
	v_mad_u32_u24 v11, v11, s34, v62
	s_lshl_b32 s34, s36, 3
	s_lshl_b32 s67, s36, 4
	s_and_b32 s75, s34, -16
	s_and_b32 s71, s67, 16
	s_mul_i32 s34, s75, 0x210
	s_mul_i32 s35, s71, 0x210
	s_add_i32 s61, s84, 0x22730
	s_add_i32 s29, s84, 0x22930
	v_ashrrev_i32_e32 v3, 2, v182
	s_lshl_b32 s74, s36, 5
	s_add_i32 s64, s84, 0x1aa90
	s_add_i32 s65, s84, 0x22830
	s_add_i32 s69, s84, 0x22a30
	s_add_i32 s66, s84, 0x22b50
	s_add_i32 s34, s84, s34
	s_add_i32 s28, s28, s35
	v_and_b32_e32 v115, -4, v3
	v_mul_u32_u24_e32 v63, 0x108, v90
	s_cmp_lt_i32 s36, 4
	v_lshlrev_b32_e32 v88, 2, v6
	v_mov_b32_e32 v89, v31
	v_or_b32_e32 v7, 1, v115
	v_lshlrev_b32_e32 v63, 1, v63
	v_and_b32_e32 v68, -16, v182
	s_cselect_b64 s[82:83], -1, 0
	v_mul_u32_u24_e32 v70, 0x48, v90
	v_lshl_add_u64 v[94:95], s[26:27], 0, v[88:89]
	s_add_i32 s26, s84, 0x1ff20
	v_or_b32_e32 v51, 2, v115
	v_lshlrev_b32_e32 v70, 1, v70
	v_add3_u32 v89, s26, v63, v68
	s_add_i32 s26, s84, 0x1aa00
	s_movk_i32 s87, 0x210
	v_cmp_gt_i32_e64 s[46:47], 33, v7
	v_ashrrev_i32_e32 v7, 4, v183
	v_or_b32_e32 v60, 3, v3
	v_cmp_gt_i32_e32 vcc, 64, v50
	v_add3_u32 v131, s26, v70, v68
	v_mad_u64_u32 v[96:97], s[26:27], v1, s87, v[2:3]
	v_mad_u64_u32 v[98:99], s[26:27], v5, s87, v[2:3]
	v_mad_u64_u32 v[100:101], s[26:27], v8, s87, v[2:3]
	v_mad_u64_u32 v[102:103], s[26:27], v13, s87, v[2:3]
	v_mul_u32_u24_e32 v2, 0x90, v4
	v_lshlrev_b32_e32 v6, 1, v50
	v_cmp_gt_i32_e64 s[48:49], 33, v51
	s_xor_b64 s[62:63], s[12:13], -1
	v_and_b32_e32 v51, -8, v7
	v_add3_u32 v69, s84, v63, v68
	s_add_i32 s93, s84, 0x22b34
	s_add_i32 s97, s84, 0x22b38
	v_writelane_b32 v254, s84, 58
	v_add3_u32 v97, s60, v2, v6
	v_cmp_gt_i32_e64 s[50:51], 33, v60
	v_mul_lo_u32 v6, v60, s87
	s_and_b64 s[84:85], s[62:63], vcc
	v_mul_lo_u32 v60, v51, s87
	v_lshl_add_u32 v99, v51, 1, v11
	v_ashrrev_i32_e32 v51, 4, v9
	s_movk_i32 s62, 0x48
	v_ashrrev_i32_e32 v9, 6, v9
	v_and_b32_e32 v62, 63, v183
	v_mul_lo_u32 v9, v9, s62
	v_add_lshl_u32 v9, v9, v62, 1
	v_add_u32_e32 v133, s60, v9
	v_add_u32_e32 v134, s64, v9
	v_ashrrev_i32_e32 v9, 6, v10
	v_add3_u32 v120, s34, v63, v68
	v_add3_u32 v121, s28, v63, v68
	v_and_b32_e32 v63, -8, v51
	v_mul_lo_u32 v9, v9, s62
	v_lshl_add_u32 v101, v63, 1, v11
	v_ashrrev_i32_e32 v11, 6, v183
	v_add_lshl_u32 v9, v9, v62, 1
	s_mul_i32 s28, s75, 0x90
	s_mul_i32 s34, s71, 0x90
	v_mul_lo_u32 v11, v11, s62
	v_add_u32_e32 v135, s60, v9
	v_add_u32_e32 v144, s64, v9
	v_ashrrev_i32_e32 v9, 6, v49
	s_add_i32 s28, s31, s28
	s_add_i32 s34, s60, s34
	v_add_u32_e32 v71, s75, v115
	v_add_lshl_u32 v11, v11, v62, 1
	v_mul_lo_u32 v9, v9, s62
	v_add3_u32 v122, s28, v70, v68
	v_add3_u32 v123, s34, v70, v68
	v_add3_u32 v72, s31, v70, v68
	v_add3_u32 v124, s64, v70, v68
	v_add3_u32 v125, s30, v70, v68
	v_cmp_gt_i32_e64 s[56:57], 4, v3
	v_cmp_gt_i32_e64 s[58:59], 0, v3
	v_or_b32_e32 v7, 7, v7
	v_mul_lo_u32 v68, v63, s87
	v_or_b32_e32 v51, 7, v51
	v_add_u32_e32 v103, s60, v11
	v_add_u32_e32 v132, s64, v11
	v_add_lshl_u32 v9, v9, v62, 1
	v_or_b32_e32 v11, 2, v71
	v_add_lshl_u32 v63, v115, s67, 2
	v_add_lshl_u32 v3, s67, v3, 2
	v_lshl_add_u32 v119, v62, 2, s29
	v_lshlrev_b32_e32 v73, 2, v182
	s_mul_i32 s81, s36, 0x2100
	s_mul_i32 s86, s36, 0x900
	v_mul_lo_u32 v2, v115, s87
	v_mul_lo_u32 v7, v7, s87
	v_mul_lo_u32 v51, v51, s87
	v_add_u32_e32 v145, s60, v9
	v_add_u32_e32 v146, s64, v9
	v_lshlrev_b32_e32 v9, 2, v71
	v_or_b32_e32 v10, 1, v71
	v_lshlrev_b32_e32 v49, 2, v11
	v_or_b32_e32 v62, 3, v71
	v_add_u32_e32 v151, s65, v63
	v_add_u32_e32 v152, s66, v63
	v_or_b32_e32 v63, 8, v63
	v_add_u32_e32 v155, s61, v3
	v_add_u32_e32 v156, s69, v3
	v_or_b32_e32 v3, 8, v3
	s_or_b32 s89, s74, 16
	v_add3_u32 v185, v50, s68, 64
	v_add3_u32 v186, v182, s68, 64
	v_add3_u32 v187, v1, s68, 64
	v_add3_u32 v188, v5, s68, 64
	v_add3_u32 v189, v8, s68, 64
	v_add3_u32 v190, v13, s68, 64
	s_add_i32 s68, s68, s75
	s_mov_b32 s80, 1
	v_cmp_gt_i32_e64 s[18:19], 15, v115
	v_cmp_gt_i32_e64 s[20:21], 14, v115
	v_cmp_gt_i32_e64 s[22:23], -1, v115
	v_cmp_gt_i32_e64 s[24:25], -2, v115
	v_add_u32_e32 v126, s61, v73
	v_add_u32_e32 v127, s65, v73
	v_add_u32_e32 v128, s29, v73
	v_lshl_add_u32 v129, v182, 1, s64
	v_add_u32_e32 v130, s66, v73
	s_mov_b32 s96, 0
	v_cmp_eq_u32_e64 s[28:29], 0, v182
	v_cmp_eq_u32_e64 s[30:31], 0, v90
	v_cmp_gt_i32_e64 s[34:35], 1, v182
	v_cmp_gt_i32_e64 s[36:37], 2, v182
	v_cmp_gt_i32_e64 s[38:39], 4, v182
	v_cmp_gt_i32_e64 s[40:41], 8, v182
	v_cmp_gt_i32_e64 s[26:27], 16, v182
	v_cmp_gt_i32_e64 s[42:43], 32, v182
	v_cmp_gt_i32_e64 s[44:45], 33, v115
	v_cmp_gt_i32_e64 s[52:53], 17, v115
	v_cmp_gt_i32_e64 s[54:55], 16, v115
	v_add_u32_e32 v147, s65, v9
	v_add_u32_e32 v148, s66, v9
	v_add_u32_e32 v149, s65, v49
	v_add_u32_e32 v150, s66, v49
	v_add_u32_e32 v153, s65, v63
	v_add_u32_e32 v154, s66, v63
	v_add_u32_e32 v157, s61, v3
	v_add_u32_e32 v158, s69, v3
	v_cmp_gt_i32_e64 s[60:61], 64, v71
	v_add_u32_e32 v159, s69, v9
	v_cmp_gt_i32_e64 s[62:63], 64, v10
	v_lshl_add_u32 v160, v10, 2, s69
	v_cmp_gt_i32_e64 s[64:65], 64, v11
	v_add_u32_e32 v161, s69, v49
	v_cmp_gt_i32_e64 s[66:67], 64, v62
	v_lshl_add_u32 v184, v62, 2, s69
	s_mulk_i32 s89, 0x90
	v_add_u32_e32 v191, s68, v115
	v_lshlrev_b32_e32 v104, 1, v4
	v_add_u32_e32 v192, v61, v60
	v_add_u32_e32 v193, v61, v7
	v_add_u32_e32 v194, v61, v68
	v_add_u32_e32 v195, v61, v51
	v_add_u32_e32 v196, s81, v69
	v_add_u32_e32 v197, s86, v72
	v_add_u32_e32 v198, v0, v2
	v_add_u32_e32 v199, v0, v6
	s_mov_b32 s75, 0
	v_mov_b32_e32 v49, v48
	v_mov_b32_e32 v50, v48
	v_mov_b32_e32 v51, v48
	v_mov_b32_e32 v60, v48
	v_mov_b32_e32 v61, v48
	v_mov_b32_e32 v62, v48
	v_mov_b32_e32 v63, v48
	v_mov_b32_e32 v72, v48
	v_mov_b32_e32 v73, v48
	v_mov_b32_e32 v74, v48
	v_mov_b32_e32 v75, v48
	v_mov_b32_e32 v68, v48
	v_mov_b32_e32 v69, v48
	v_mov_b32_e32 v70, v48
	v_mov_b32_e32 v71, v48
	v_mov_b32_e32 v76, v48
	v_mov_b32_e32 v77, v48
	v_mov_b32_e32 v78, v48
	v_mov_b32_e32 v79, v48
	v_mov_b32_e32 v80, v48
	v_mov_b32_e32 v81, v48
	v_mov_b32_e32 v82, v48
	v_mov_b32_e32 v83, v48
	s_waitcnt vmcnt(0) lgkmcnt(0)
	s_barrier
	s_branch .LBB0_1584

; #define LAS __attribute__((address_space(3)))
; __device__ __forceinline__ void mlstm_task(const Ctx& c, int p, int l, int q, int h, int slab) {
;     ...
;     for (int ck = 0; ck < nch; ++ck) {
;         const int rbase = sq.row0 + ck * 64;
; #pragma unroll
;         for (int i = 0; i < 4; ++i) {
;             const int piece = tid + 512 * i, t = piece >> 5, pc = piece & 31;
;             *(LAS u32x4*)(Qs + t * 264 + 8 * pc) = pq[i]; *(LAS u32x4*)(Ks + t * 264 + 8 * pc) = pk[i];
;         }
;         *(LAS u32x4*)(St + (tid >> 3) * 72 + 8 * (tid & 7)) = psl;
;         if (tid < 256) {
;             const int t = tid >> 2, pc = tid & 3; const u32x4 vv = pvv;
;             const unsigned vw[4] = {vv.x, vv.y, vv.z, vv.w};
; #pragma unroll
;             for (int e = 0; e < 4; ++e) { VT[(8 * pc + 2 * e) * 72 + t] = (bf16_t)(vw[e] & 0xffffu); VT[(8 * pc + 2 * e + 1) * 72 + t] = (bf16_t)(vw[e] >> 16); }
;         }
.LBB0_1584:
	s_waitcnt vmcnt(4)
	s_and_saveexec_b64 s[68:69], s[14:15]
	s_cbranch_execz .Lml_top_a
	ds_write_b16 v97, v56
	ds_write_b16_d16_hi v97, v56 offset:144
	ds_write_b16 v97, v57 offset:288
	ds_write_b16_d16_hi v97, v57 offset:432
	ds_write_b16 v97, v58 offset:576
	ds_write_b16_d16_hi v97, v58 offset:720
	ds_write_b16 v97, v59 offset:864
	ds_write_b16_d16_hi v97, v59 offset:1008

; __device__ __forceinline__ bf16_t f2bf(float f) { unsigned u = __float_as_uint(f); u += 0x7FFFu + ((u >> 16) & 1u); return (bf16_t)(u >> 16); }
; __device__ __forceinline__ void mlstm_task(const Ctx& c, int p, int l, int q, int h, int slab) {
;     ...
; #pragma unroll
;         for (int vi = 0; vi < 3; ++vi)
; #pragma unroll
;             for (int e = 0; e < 2; ++e)
; #pragma unroll
;                 for (int r = 0; r < 4; ++r) { const int vloc = 16 * vi + (lane >> 4) * 4 + r; if (vloc <= 32) Cs[vloc * 264 + 16 * (2 * w + e) + (lane & 15)] = f2bf(cacc[vi][e][r]); }
.LBB0_1640:
	v_cvt_pk_bf16_f32 v4, v68, v72
	v_cvt_pk_bf16_f32 v5, v69, v73
	v_cvt_pk_bf16_f32 v6, v70, v74
	v_cvt_pk_bf16_f32 v7, v71, v75
	v_cvt_pk_bf16_f32 v8, v60, v48
	v_cvt_pk_bf16_f32 v9, v61, v49
	v_cvt_pk_bf16_f32 v10, v62, v50
	v_cvt_pk_bf16_f32 v11, v63, v51
	v_cvt_pk_bf16_f32 v0, v80, v76
	v_cvt_pk_bf16_f32 v1, v81, v77
	v_cvt_pk_bf16_f32 v2, v82, v78
	v_cvt_pk_bf16_f32 v3, v83, v79
	s_and_saveexec_b64 s[68:69], s[44:45]
	ds_write_b16 v198, v0
	ds_write_b16_d16_hi v198, v0 offset:32
	s_or_b64 exec, exec, s[68:69]
	s_and_saveexec_b64 s[68:69], s[46:47]
	ds_write_b16 v198, v1 offset:528
	ds_write_b16_d16_hi v198, v1 offset:560
	s_or_b64 exec, exec, s[68:69]
	s_and_saveexec_b64 s[68:69], s[48:49]
	ds_write_b16 v198, v2 offset:1056
	ds_write_b16_d16_hi v198, v2 offset:1088
	s_or_b64 exec, exec, s[68:69]
	s_and_saveexec_b64 s[68:69], s[50:51]
	ds_write_b16 v199, v3
	ds_write_b16_d16_hi v199, v3 offset:32
	s_or_b64 exec, exec, s[68:69]
	s_and_saveexec_b64 s[68:69], s[52:53]
	ds_write_b16 v198, v4 offset:8448
	ds_write_b16_d16_hi v198, v4 offset:8480
	s_or_b64 exec, exec, s[68:69]
	s_and_saveexec_b64 s[68:69], s[54:55]
	ds_write_b16 v198, v5 offset:8976
	ds_write_b16_d16_hi v198, v5 offset:9008
	s_or_b64 exec, exec, s[68:69]
	s_and_saveexec_b64 s[68:69], s[18:19]
	ds_write_b16 v198, v6 offset:9504
	ds_write_b16_d16_hi v198, v6 offset:9536
	s_or_b64 exec, exec, s[68:69]
	s_and_saveexec_b64 s[68:69], s[20:21]
	ds_write_b16 v198, v7 offset:10032
	ds_write_b16_d16_hi v198, v7 offset:10064
	s_or_b64 exec, exec, s[68:69]
	s_and_saveexec_b64 s[68:69], s[56:57]
	ds_write_b16 v198, v8 offset:16896
	ds_write_b16_d16_hi v198, v8 offset:16928
	s_or_b64 exec, exec, s[68:69]
	s_and_saveexec_b64 s[68:69], s[58:59]
	ds_write_b16 v198, v9 offset:17424
	ds_write_b16_d16_hi v198, v9 offset:17456
	s_or_b64 exec, exec, s[68:69]
	s_and_saveexec_b64 s[68:69], s[22:23]
	ds_write_b16 v198, v10 offset:17952
	ds_write_b16_d16_hi v198, v10 offset:17984
	s_or_b64 exec, exec, s[68:69]
	s_and_saveexec_b64 s[68:69], s[24:25]
	ds_write_b16 v198, v11 offset:18480
	ds_write_b16_d16_hi v198, v11 offset:18512
	s_or_b64 exec, exec, s[68:69]

; __device__ __forceinline__ bf16_t f2bf(float f) { unsigned u = __float_as_uint(f); u += 0x7FFFu + ((u >> 16) & 1u); return (bf16_t)(u >> 16); }
; __device__ __forceinline__ void mlstm_task(const Ctx& c, int p, int l, int q, int h, int slab) {
;     ...
;                 for (int r = 0; r < 4; ++r) { const int vloc = 16 * vi + (lane >> 4) * 4 + r; if (vloc <= 32) Cs[vloc * 264 + 16 * (2 * w + e) + (lane & 15)] = f2bf(cacc[vi][e][r]); }
;     ...
;         for (int r = 0; r < 4; ++r) {
;             const int t = 16 * ti + (lane >> 4) * 4 + r;
;             if (t < nvalid) Z[(size_t)(rbase + t) * ZW + C_V + 256 * h + slab * 32 + 16 * vj + (lane & 15)] = f2bf(num[r] * __builtin_amdgcn_rcpf(dd[t]));
;         }
.LBB0_1638:
	ds_read_b32 v1, v161
	v_mul_f32_e32 v0, v6, v108
	v_fmac_f32_e32 v0, v2, v106
	v_add3_u32 v4, v191, s96, 2
	s_lshl_b32 s90, s88, 1
	s_waitcnt lgkmcnt(0)
	v_rcp_f32_e32 v1, v1
	v_mov_b32_e32 v9, v31
	v_mul_f32_e32 v0, v0, v1
	v_bfe_u32 v1, v0, 16, 1
	v_add3_u32 v2, v0, v1, s1
	v_mov_b64_e32 v[0:1], s[72:73]
	v_mad_i64_i32 v[0:1], s[86:87], v4, s33, v[0:1]
	v_lshl_add_u64 v[0:1], v[0:1], 0, s[90:91]
	s_lshl_b32 s90, s92, 1
	v_lshl_add_u64 v[0:1], v[0:1], 0, s[90:91]
	s_lshl_b32 s90, s71, 1
	v_lshl_add_u64 v[0:1], v[0:1], 0, s[90:91]
	v_lshl_add_u64 v[0:1], v[0:1], 0, v[8:9]
	v_add_co_u32_e32 v0, vcc, 0x1000, v0
	s_nop 1
	v_addc_co_u32_e32 v1, vcc, 0, v1, vcc
	global_store_short_d16_hi v[0:1], v2, off offset:2048
	s_or_b64 exec, exec, s[68:69]
	s_and_saveexec_b64 s[68:69], s[66:67]
	s_cbranch_execnz .LBB0_1667
	s_branch .LBB0_1668
.LBB0_1664:
	s_or_b64 exec, exec, s[68:69]
	s_and_saveexec_b64 s[68:69], s[62:63]
	s_cbranch_execz .LBB0_1637
